# rope tables stored in lane-order layout so the q/k epilogue table loads are fully coalesced; epilogue loads pipelined
# speedup vs baseline: 1.0086x; 1.0086x over previous
.LBB0_116:
	s_mov_b32 s0, 0x80000
	v_cmp_gt_i32_e32 vcc, s0, v198
	s_and_saveexec_b64 s[0:1], vcc
	v_readlane_b32 s63, v254, 2
	s_cbranch_execz .LBB0_119
	s_mov_b32 s2, 0x979a371
	v_cvt_f64_u32_e32 v[2:3], v2
	s_mov_b32 s3, 0xbfda934f
	v_mul_f64 v[2:3], v[2:3], s[2:3]
	v_rndne_f64_e32 v[4:5], v[2:3]
	s_mov_b32 s2, 0x3b39803f
	v_add_f64 v[6:7], v[2:3], -v[4:5]
	s_mov_b32 s3, 0x3c7abc9e
	v_mul_f64 v[8:9], v[6:7], s[2:3]
	s_mov_b32 s2, 0xfefa39ef
	s_mov_b32 s3, 0x3fe62e42
	v_fmac_f64_e32 v[8:9], s[2:3], v[6:7]
	s_mov_b32 s2, 0x6a5dcb37
	v_mov_b32_e32 v6, 0xfca7ab0c
	v_mov_b32_e32 v7, 0x3e928af3
	s_mov_b32 s3, 0x3e5ade15
	v_fmac_f64_e32 v[6:7], s[2:3], v[8:9]
	v_mov_b32_e32 v10, 0x623fde64
	v_mov_b32_e32 v11, 0x3ec71dee
	v_fmac_f64_e32 v[10:11], v[8:9], v[6:7]
	v_mov_b32_e32 v6, 0x7c89e6b0
	v_mov_b32_e32 v7, 0x3efa0199
	v_fmac_f64_e32 v[6:7], v[8:9], v[10:11]
	v_mov_b32_e32 v10, 0x14761f6e
	v_mov_b32_e32 v11, 0x3f2a01a0
	v_fmac_f64_e32 v[10:11], v[8:9], v[6:7]
	v_mov_b32_e32 v6, 0x1852b7b0
	v_mov_b32_e32 v7, 0x3f56c16c
	v_fmac_f64_e32 v[6:7], v[8:9], v[10:11]
	v_mov_b32_e32 v10, 0x11122322
	v_mov_b32_e32 v11, 0x3f811111
	v_fmac_f64_e32 v[10:11], v[8:9], v[6:7]
	v_mov_b32_e32 v6, 0x555502a1
	v_mov_b32_e32 v7, 0x3fa55555
	v_fmac_f64_e32 v[6:7], v[8:9], v[10:11]
	v_mov_b32_e32 v10, 0x55555511
	v_mov_b32_e32 v11, 0x3fc55555
	v_fmac_f64_e32 v[10:11], v[8:9], v[6:7]
	v_mov_b32_e32 v6, 11
	v_mov_b32_e32 v7, 0x3fe00000
	s_mov_b32 s2, 0
	v_fmac_f64_e32 v[6:7], v[8:9], v[10:11]
	s_mov_b32 s3, 0x40900000
	v_fma_f64 v[6:7], v[8:9], v[6:7], 1.0
	v_cmp_nlt_f64_e32 vcc, s[2:3], v[2:3]
	s_mov_b32 s2, 0
	v_fma_f64 v[6:7], v[8:9], v[6:7], 1.0
	v_cvt_i32_f64_e32 v4, v[4:5]
	s_mov_b32 s3, 0xc090cc00
	v_ldexp_f64 v[4:5], v[6:7], v4
	v_mov_b32_e32 v6, 0x7ff00000
	v_cmp_ngt_f64_e64 s[2:3], s[2:3], v[2:3]
	v_cndmask_b32_e32 v5, v6, v5, vcc
	s_and_b64 vcc, s[2:3], vcc
	v_cndmask_b32_e64 v3, 0, v5, s[2:3]
	v_cndmask_b32_e32 v2, 0, v4, vcc
	v_cvt_f32_f64_e32 v4, v[2:3]
	v_lshl_add_u64 v[2:3], v[198:199], 2, s[82:83]
	s_mov_b64 s[2:3], 0xc00000
	s_ashr_i32 s7, s6, 31
	s_mov_b32 s8, 0x6dc9c883
	v_lshl_add_u64 v[2:3], v[2:3], 0, s[2:3]
	s_lshl_b64 s[2:3], s[6:7], 2
	s_mov_b64 s[4:5], 0
	s_mov_b32 s9, 0x3fc45f30
	s_mov_b32 s7, 0x7ffff
	s_add_u32 s98, s82, 0xc00000
	s_addc_u32 s99, s83, 0
	s_add_u32 s100, s82, 0xe00000
	s_addc_u32 s101, s83, 0
.LBB0_118:
	v_and_b32_e32 v232, 0xfffffe03, v198
	v_bfe_u32 v233, v198, 5, 4
	v_lshl_or_b32 v232, v233, 2, v232
	v_bfe_u32 v233, v198, 3, 2
	v_lshl_or_b32 v232, v233, 6, v232
	v_bfe_u32 v233, v198, 2, 1
	v_lshl_or_b32 v232, v233, 8, v232
	v_lshlrev_b32_e32 v232, 2, v232
	v_ashrrev_i32_e32 v6, 5, v198
	v_ashrrev_i32_e32 v7, 31, v6
	v_lshl_add_u64 v[6:7], v[6:7], 2, s[48:49]
	global_load_dword v5, v[6:7], off
	v_add_co_u32_e32 v6, vcc, 0x200000, v2
	v_add_u32_e32 v198, s6, v198
	s_nop 0
	v_addc_co_u32_e32 v7, vcc, 0, v3, vcc
	v_cmp_lt_i32_e32 vcc, s7, v198
	s_or_b64 s[4:5], vcc, s[4:5]
	s_waitcnt vmcnt(0)
	v_cvt_f32_i32_e32 v5, v5
	v_mul_f32_e32 v5, v4, v5
	v_cvt_f64_f32_e32 v[8:9], v5
	v_mul_f64 v[10:11], v[8:9], s[8:9]
	v_rndne_f64_e32 v[10:11], v[10:11]
	v_fma_f64 v[8:9], v[8:9], s[8:9], -v[10:11]
	v_cvt_f32_f64_e32 v5, v[8:9]
	v_cos_f32_e32 v8, v5
	v_sin_f32_e32 v5, v5
	global_store_dword v232, v8, s[98:99]
	global_store_dword v232, v5, s[100:101]
	v_lshl_add_u64 v[2:3], v[2:3], 0, s[2:3]
	s_andn2_b64 exec, exec, s[4:5]
	s_cbranch_execnz .LBB0_118

.LBB0_198:
	s_andn2_b64 vcc, exec, s[4:5]
	s_cbranch_vccnz .LBB0_200
	v_lshlrev_b32_e32 v163, 7, v162
	v_lshl_or_b32 v138, v161, 5, v163
	v_and_b32_e32 v249, 15, v162
	v_and_b32_e32 v248, 0xfffffff0, v162
	v_lshlrev_b32_e32 v248, 7, v248
	v_lshl_or_b32 v248, v249, 4, v248
	v_lshl_or_b32 v248, v161, 8, v248
	s_add_u32 s98, s82, 0xc00000
	s_addc_u32 s99, s83, 0
	s_add_u32 s100, s82, 0xe00000
	s_addc_u32 s101, s83, 0
	global_load_dwordx4 v[184:187], v248, s[98:99]
	global_load_dwordx4 v[188:191], v248, s[100:101]
	global_load_dwordx4 v[192:195], v248, s[98:99] offset:1024
	global_load_dwordx4 v[196:199], v248, s[100:101] offset:1024
	v_add_u32_e32 v249, 0x800, v248
	global_load_dwordx4 v[200:203], v249, s[98:99]
	global_load_dwordx4 v[204:207], v249, s[100:101]
	global_load_dwordx4 v[208:211], v249, s[98:99] offset:1024
	global_load_dwordx4 v[212:215], v249, s[100:101] offset:1024
	v_add_u32_e32 v250, 0x1000, v248
	global_load_dwordx4 v[216:219], v250, s[98:99]
	global_load_dwordx4 v[220:223], v250, s[100:101]
	global_load_dwordx4 v[224:227], v250, s[98:99] offset:1024
	global_load_dwordx4 v[228:231], v250, s[100:101] offset:1024
	v_add_u32_e32 v251, 0x1800, v248
	global_load_dwordx4 v[232:235], v251, s[98:99]
	global_load_dwordx4 v[236:239], v251, s[100:101]
	global_load_dwordx4 v[240:243], v251, s[98:99] offset:1024
	global_load_dwordx4 v[244:247], v251, s[100:101] offset:1024
	v_lshl_add_u64 v[148:149], s[82:83], 0, v[138:139]
	v_add_co_u32_e32 v150, vcc, s51, v148
	s_cmp_lt_u32 s18, 10
	s_nop 0
	v_addc_co_u32_e32 v151, vcc, 0, v149, vcc
	v_add_co_u32_e32 v152, vcc, s50, v148
	s_nop 0
	v_addc_co_u32_e32 v153, vcc, 0, v149, vcc
	s_cselect_b64 vcc, -1, 0
	v_cndmask_b32_e32 v138, 1.0, v160, vcc
	v_add_co_u32_e64 v154, s[4:5], s48, v148
	v_mov_b32_e32 v181, v139
	s_nop 0
	v_addc_co_u32_e64 v155, s[4:5], 0, v149, s[4:5]
	v_add_co_u32_e64 v178, s[4:5], s49, v148
	s_waitcnt vmcnt(12)
	v_pk_mul_f32 v[166:167], v[138:139], v[186:187] op_sel_hi:[0,1]
	v_pk_mul_f32 v[164:165], v[138:139], v[184:185] op_sel_hi:[0,1]
	v_addc_co_u32_e64 v179, s[4:5], 0, v149, s[4:5]
	v_pk_mul_f32 v[170:171], v[138:139], v[190:191] op_sel_hi:[0,1]
	v_pk_mul_f32 v[168:169], v[138:139], v[188:189] op_sel_hi:[0,1]
	v_pk_mul_f32 v[172:173], v[120:121], v[170:171]
	v_pk_mul_f32 v[174:175], v[118:119], v[168:169]
	v_pk_mul_f32 v[168:169], v[126:127], v[168:169]
	v_pk_mul_f32 v[170:171], v[128:129], v[170:171]
	v_pk_fma_f32 v[172:173], v[128:129], v[166:167], v[172:173] neg_lo:[0,0,1] neg_hi:[0,0,1]
	v_pk_fma_f32 v[174:175], v[126:127], v[164:165], v[174:175] neg_lo:[0,0,1] neg_hi:[0,0,1]
	v_pk_fma_f32 v[168:169], v[118:119], v[164:165], v[168:169]
	v_pk_fma_f32 v[166:167], v[120:121], v[166:167], v[170:171]
	v_cvt_pk_bf16_f32 v164, v174, v175
	v_cvt_pk_bf16_f32 v165, v172, v173
	v_cvt_pk_bf16_f32 v168, v168, v169
	s_and_b64 s[4:5], vcc, exec
	v_cvt_pk_bf16_f32 v169, v166, v167
	s_cselect_b32 s4, s47, 0x6000000
	s_lshl_b32 s5, s18, 2
	s_and_b32 s5, s5, 4
	v_lshl_or_b32 v166, v161, 4, s4
	s_or_b32 s4, s11, s5
	v_lshl_or_b32 v166, s4, 21, v166
	v_add_u32_e32 v180, v166, v163
	v_pk_mul_f32 v[166:167], v[138:139], v[194:195] op_sel_hi:[0,1]
	v_pk_mul_f32 v[172:173], v[138:139], v[198:199] op_sel_hi:[0,1]
	v_pk_mul_f32 v[174:175], v[138:139], v[196:197] op_sel_hi:[0,1]
	v_pk_mul_f32 v[170:171], v[138:139], v[192:193] op_sel_hi:[0,1]
	v_pk_mul_f32 v[176:177], v[116:117], v[172:173]
	v_pk_mul_f32 v[182:183], v[114:115], v[174:175]
	v_pk_mul_f32 v[172:173], v[124:125], v[172:173]
	v_pk_mul_f32 v[174:175], v[122:123], v[174:175]
	v_pk_fma_f32 v[176:177], v[124:125], v[166:167], v[176:177] neg_lo:[0,0,1] neg_hi:[0,0,1]
	v_pk_fma_f32 v[182:183], v[122:123], v[170:171], v[182:183] neg_lo:[0,0,1] neg_hi:[0,0,1]
	v_pk_fma_f32 v[172:173], v[116:117], v[166:167], v[172:173]
	v_pk_fma_f32 v[170:171], v[114:115], v[170:171], v[174:175]
	v_cvt_pk_bf16_f32 v166, v182, v183
	v_cvt_pk_bf16_f32 v167, v176, v177
	s_nop 0
	v_cvt_pk_bf16_f32 v170, v170, v171
	v_cvt_pk_bf16_f32 v171, v172, v173
	global_store_dwordx4 v180, v[164:167], s[82:83]
	global_store_dwordx4 v180, v[168:171], s[82:83] offset:64
	v_add_u32_e32 v252, 0x4000, v248
	global_load_dwordx4 v[184:187], v252, s[98:99]
	global_load_dwordx4 v[188:191], v252, s[100:101]
	global_load_dwordx4 v[192:195], v252, s[98:99] offset:1024
	global_load_dwordx4 v[196:199], v252, s[100:101] offset:1024
	s_nop 0
	s_waitcnt vmcnt(14)
	v_pk_mul_f32 v[166:167], v[138:139], v[202:203] op_sel_hi:[0,1]
	v_pk_mul_f32 v[164:165], v[138:139], v[200:201] op_sel_hi:[0,1]
	v_pk_mul_f32 v[168:169], v[138:139], v[204:205] op_sel_hi:[0,1]
	v_pk_mul_f32 v[170:171], v[138:139], v[206:207] op_sel_hi:[0,1]
	v_pk_mul_f32 v[174:175], v[102:103], v[168:169]
	v_pk_mul_f32 v[176:177], v[104:105], v[166:167]
	v_pk_mul_f32 v[182:183], v[102:103], v[164:165]
	v_pk_mul_f32 v[172:173], v[104:105], v[170:171]
	v_pk_fma_f32 v[164:165], v[110:111], v[164:165], v[174:175] neg_lo:[0,0,1] neg_hi:[0,0,1]
	v_pk_fma_f32 v[170:171], v[112:113], v[170:171], v[176:177]
	v_pk_fma_f32 v[168:169], v[110:111], v[168:169], v[182:183]
	v_pk_fma_f32 v[166:167], v[112:113], v[166:167], v[172:173] neg_lo:[0,0,1] neg_hi:[0,0,1]
	v_cvt_pk_bf16_f32 v164, v164, v165
	s_nop 0
	v_cvt_pk_bf16_f32 v165, v166, v167
	v_cvt_pk_bf16_f32 v168, v168, v169
	v_cvt_pk_bf16_f32 v169, v170, v171
	v_pk_mul_f32 v[154:155], v[138:139], v[210:211] op_sel_hi:[0,1]
	v_pk_mul_f32 v[166:167], v[138:139], v[208:209] op_sel_hi:[0,1]
	v_pk_mul_f32 v[170:171], v[138:139], v[214:215] op_sel_hi:[0,1]
	v_pk_mul_f32 v[172:173], v[138:139], v[212:213] op_sel_hi:[0,1]
	v_pk_mul_f32 v[174:175], v[100:101], v[170:171]
	v_pk_mul_f32 v[176:177], v[98:99], v[172:173]
	v_pk_mul_f32 v[170:171], v[108:109], v[170:171]
	v_pk_mul_f32 v[172:173], v[106:107], v[172:173]
	v_pk_fma_f32 v[174:175], v[108:109], v[154:155], v[174:175] neg_lo:[0,0,1] neg_hi:[0,0,1]
	v_pk_fma_f32 v[176:177], v[106:107], v[166:167], v[176:177] neg_lo:[0,0,1] neg_hi:[0,0,1]
	v_pk_fma_f32 v[154:155], v[100:101], v[154:155], v[170:171]
	v_pk_fma_f32 v[170:171], v[98:99], v[166:167], v[172:173]
	v_cvt_pk_bf16_f32 v166, v176, v177
	v_cvt_pk_bf16_f32 v167, v174, v175
	s_nop 0
	v_cvt_pk_bf16_f32 v170, v170, v171
	v_cvt_pk_bf16_f32 v171, v154, v155
	global_store_dwordx4 v180, v[164:167], s[82:83] offset:2048
	global_store_dwordx4 v180, v[168:171], s[82:83] offset:2112
	v_add_u32_e32 v252, 0x4800, v248
	global_load_dwordx4 v[200:203], v252, s[98:99]
	global_load_dwordx4 v[204:207], v252, s[100:101]
	global_load_dwordx4 v[208:211], v252, s[98:99] offset:1024
	global_load_dwordx4 v[212:215], v252, s[100:101] offset:1024
	s_nop 0
	s_waitcnt vmcnt(16)
	v_pk_mul_f32 v[164:165], v[138:139], v[216:217] op_sel_hi:[0,1]
	v_pk_mul_f32 v[168:169], v[138:139], v[220:221] op_sel_hi:[0,1]
	v_pk_mul_f32 v[154:155], v[138:139], v[218:219] op_sel_hi:[0,1]
	v_pk_mul_f32 v[166:167], v[138:139], v[222:223] op_sel_hi:[0,1]
	v_pk_mul_f32 v[172:173], v[86:87], v[168:169]
	v_pk_mul_f32 v[176:177], v[86:87], v[164:165]
	v_pk_mul_f32 v[170:171], v[88:89], v[166:167]
	v_pk_mul_f32 v[174:175], v[88:89], v[154:155]
	v_pk_fma_f32 v[164:165], v[94:95], v[164:165], v[172:173] neg_lo:[0,0,1] neg_hi:[0,0,1]
	v_pk_fma_f32 v[168:169], v[94:95], v[168:169], v[176:177]
	v_pk_fma_f32 v[154:155], v[96:97], v[154:155], v[170:171] neg_lo:[0,0,1] neg_hi:[0,0,1]
	v_pk_fma_f32 v[166:167], v[96:97], v[166:167], v[174:175]
	v_cvt_pk_bf16_f32 v164, v164, v165
	v_cvt_pk_bf16_f32 v165, v154, v155
	v_cvt_pk_bf16_f32 v168, v168, v169
	v_lshl_add_u64 v[154:155], s[82:83], 0, v[180:181]
	v_cvt_pk_bf16_f32 v169, v166, v167
	v_add_co_u32_e32 v178, vcc, s45, v154
	v_pk_mul_f32 v[166:167], v[138:139], v[226:227] op_sel_hi:[0,1]
	v_pk_mul_f32 v[172:173], v[138:139], v[230:231] op_sel_hi:[0,1]
	v_pk_mul_f32 v[174:175], v[138:139], v[228:229] op_sel_hi:[0,1]
	v_pk_mul_f32 v[170:171], v[138:139], v[224:225] op_sel_hi:[0,1]
	v_pk_mul_f32 v[176:177], v[84:85], v[172:173]
	v_pk_mul_f32 v[180:181], v[82:83], v[174:175]
	v_pk_mul_f32 v[172:173], v[92:93], v[172:173]
	v_pk_mul_f32 v[174:175], v[90:91], v[174:175]
	v_addc_co_u32_e32 v179, vcc, 0, v155, vcc
	v_pk_fma_f32 v[176:177], v[92:93], v[166:167], v[176:177] neg_lo:[0,0,1] neg_hi:[0,0,1]
	v_pk_fma_f32 v[180:181], v[90:91], v[170:171], v[180:181] neg_lo:[0,0,1] neg_hi:[0,0,1]
	v_pk_fma_f32 v[172:173], v[84:85], v[166:167], v[172:173]
	v_pk_fma_f32 v[170:171], v[82:83], v[170:171], v[174:175]
	v_cvt_pk_bf16_f32 v166, v180, v181
	v_cvt_pk_bf16_f32 v167, v176, v177
	s_nop 0
	v_cvt_pk_bf16_f32 v170, v170, v171
	v_cvt_pk_bf16_f32 v171, v172, v173
	global_store_dwordx4 v[178:179], v[164:167], off
	global_store_dwordx4 v[178:179], v[168:171], off offset:64
	v_add_u32_e32 v252, 0x5000, v248
	global_load_dwordx4 v[216:219], v252, s[98:99]
	global_load_dwordx4 v[220:223], v252, s[100:101]
	global_load_dwordx4 v[224:227], v252, s[98:99] offset:1024
	global_load_dwordx4 v[228:231], v252, s[100:101] offset:1024
	s_nop 0
	s_waitcnt vmcnt(18)
	v_pk_mul_f32 v[166:167], v[138:139], v[234:235] op_sel_hi:[0,1]
	v_pk_mul_f32 v[164:165], v[138:139], v[232:233] op_sel_hi:[0,1]
	v_pk_mul_f32 v[168:169], v[138:139], v[236:237] op_sel_hi:[0,1]
	v_pk_mul_f32 v[170:171], v[138:139], v[238:239] op_sel_hi:[0,1]
	v_pk_mul_f32 v[174:175], v[70:71], v[168:169]
	v_pk_mul_f32 v[176:177], v[72:73], v[166:167]
	v_pk_mul_f32 v[180:181], v[70:71], v[164:165]
	v_pk_mul_f32 v[172:173], v[72:73], v[170:171]
	v_pk_fma_f32 v[164:165], v[78:79], v[164:165], v[174:175] neg_lo:[0,0,1] neg_hi:[0,0,1]
	v_pk_fma_f32 v[170:171], v[80:81], v[170:171], v[176:177]
	v_pk_fma_f32 v[168:169], v[78:79], v[168:169], v[180:181]
	v_pk_fma_f32 v[166:167], v[80:81], v[166:167], v[172:173] neg_lo:[0,0,1] neg_hi:[0,0,1]
	v_cvt_pk_bf16_f32 v164, v164, v165
	s_nop 0
	v_cvt_pk_bf16_f32 v165, v166, v167
	v_cvt_pk_bf16_f32 v168, v168, v169
	v_cvt_pk_bf16_f32 v169, v170, v171
	v_add_co_u32_e32 v150, vcc, s55, v148
	v_pk_mul_f32 v[152:153], v[138:139], v[242:243] op_sel_hi:[0,1]
	v_pk_mul_f32 v[166:167], v[138:139], v[240:241] op_sel_hi:[0,1]
	v_pk_mul_f32 v[170:171], v[138:139], v[246:247] op_sel_hi:[0,1]
	v_pk_mul_f32 v[172:173], v[138:139], v[244:245] op_sel_hi:[0,1]
	v_pk_mul_f32 v[174:175], v[68:69], v[170:171]
	v_pk_mul_f32 v[176:177], v[66:67], v[172:173]
	v_pk_mul_f32 v[170:171], v[76:77], v[170:171]
	v_pk_mul_f32 v[172:173], v[74:75], v[172:173]
	v_addc_co_u32_e32 v151, vcc, 0, v149, vcc
	v_pk_fma_f32 v[174:175], v[76:77], v[152:153], v[174:175] neg_lo:[0,0,1] neg_hi:[0,0,1]
	v_pk_fma_f32 v[176:177], v[74:75], v[166:167], v[176:177] neg_lo:[0,0,1] neg_hi:[0,0,1]
	v_pk_fma_f32 v[152:153], v[68:69], v[152:153], v[170:171]
	v_pk_fma_f32 v[170:171], v[66:67], v[166:167], v[172:173]
	v_cvt_pk_bf16_f32 v166, v176, v177
	v_cvt_pk_bf16_f32 v167, v174, v175
	s_nop 0
	v_cvt_pk_bf16_f32 v170, v170, v171
	v_cvt_pk_bf16_f32 v171, v152, v153
	global_store_dwordx4 v[178:179], v[164:167], off offset:2048
	global_store_dwordx4 v[178:179], v[168:171], off offset:2112
	v_add_u32_e32 v252, 0x5800, v248
	global_load_dwordx4 v[232:235], v252, s[98:99]
	global_load_dwordx4 v[236:239], v252, s[100:101]
	global_load_dwordx4 v[240:243], v252, s[98:99] offset:1024
	global_load_dwordx4 v[244:247], v252, s[100:101] offset:1024
	v_add_co_u32_e32 v152, vcc, s54, v148
	s_nop 0
	v_addc_co_u32_e32 v153, vcc, 0, v149, vcc
	v_add_co_u32_e32 v178, vcc, s52, v148
	s_waitcnt vmcnt(18)
	v_pk_mul_f32 v[166:167], v[138:139], v[186:187] op_sel_hi:[0,1]
	v_addc_co_u32_e32 v179, vcc, 0, v149, vcc
	v_pk_mul_f32 v[170:171], v[138:139], v[190:191] op_sel_hi:[0,1]
	v_pk_mul_f32 v[168:169], v[138:139], v[188:189] op_sel_hi:[0,1]
	v_pk_mul_f32 v[164:165], v[138:139], v[184:185] op_sel_hi:[0,1]
	v_pk_mul_f32 v[172:173], v[56:57], v[170:171]
	v_pk_mul_f32 v[174:175], v[54:55], v[168:169]
	v_pk_mul_f32 v[168:169], v[62:63], v[168:169]
	v_add_co_u32_e32 v180, vcc, s53, v148
	v_pk_mul_f32 v[170:171], v[64:65], v[170:171]
	v_pk_fma_f32 v[172:173], v[64:65], v[166:167], v[172:173] neg_lo:[0,0,1] neg_hi:[0,0,1]
	v_pk_fma_f32 v[174:175], v[62:63], v[164:165], v[174:175] neg_lo:[0,0,1] neg_hi:[0,0,1]
	v_pk_fma_f32 v[168:169], v[54:55], v[164:165], v[168:169]
	v_addc_co_u32_e32 v181, vcc, 0, v149, vcc
	v_pk_fma_f32 v[166:167], v[56:57], v[166:167], v[170:171]
	v_cvt_pk_bf16_f32 v164, v174, v175
	v_cvt_pk_bf16_f32 v165, v172, v173
	v_cvt_pk_bf16_f32 v168, v168, v169
	v_add_co_u32_e32 v182, vcc, s38, v154
	v_cvt_pk_bf16_f32 v169, v166, v167
	v_addc_co_u32_e32 v183, vcc, 0, v155, vcc
	v_add_co_u32_e32 v148, vcc, s46, v154
	v_pk_mul_f32 v[166:167], v[138:139], v[192:193] op_sel_hi:[0,1]
	v_addc_co_u32_e32 v149, vcc, 0, v155, vcc
	v_pk_mul_f32 v[154:155], v[138:139], v[194:195] op_sel_hi:[0,1]
	v_pk_mul_f32 v[170:171], v[138:139], v[198:199] op_sel_hi:[0,1]
	v_pk_mul_f32 v[172:173], v[138:139], v[196:197] op_sel_hi:[0,1]
	v_pk_mul_f32 v[174:175], v[52:53], v[170:171]
	v_pk_mul_f32 v[176:177], v[50:51], v[172:173]
	v_pk_mul_f32 v[170:171], v[60:61], v[170:171]
	v_pk_mul_f32 v[172:173], v[58:59], v[172:173]
	v_pk_fma_f32 v[174:175], v[60:61], v[154:155], v[174:175] neg_lo:[0,0,1] neg_hi:[0,0,1]
	v_pk_fma_f32 v[176:177], v[58:59], v[166:167], v[176:177] neg_lo:[0,0,1] neg_hi:[0,0,1]
	v_pk_fma_f32 v[154:155], v[52:53], v[154:155], v[170:171]
	v_pk_fma_f32 v[170:171], v[50:51], v[166:167], v[172:173]
	v_cvt_pk_bf16_f32 v166, v176, v177
	v_cvt_pk_bf16_f32 v167, v174, v175
	s_nop 0
	v_cvt_pk_bf16_f32 v170, v170, v171
	v_cvt_pk_bf16_f32 v171, v154, v155
	global_store_dwordx4 v[148:149], v[164:167], off offset:-4096
	global_store_dwordx4 v[182:183], v[168:171], off offset:64
	s_nop 0
	s_waitcnt vmcnt(14)
	v_pk_mul_f32 v[164:165], v[138:139], v[200:201] op_sel_hi:[0,1]
	v_pk_mul_f32 v[168:169], v[138:139], v[204:205] op_sel_hi:[0,1]
	v_pk_mul_f32 v[154:155], v[138:139], v[202:203] op_sel_hi:[0,1]
	v_pk_mul_f32 v[166:167], v[138:139], v[206:207] op_sel_hi:[0,1]
	v_pk_mul_f32 v[172:173], v[38:39], v[168:169]
	v_pk_mul_f32 v[176:177], v[38:39], v[164:165]
	v_pk_mul_f32 v[170:171], v[40:41], v[166:167]
	v_pk_mul_f32 v[174:175], v[40:41], v[154:155]
	v_pk_fma_f32 v[164:165], v[46:47], v[164:165], v[172:173] neg_lo:[0,0,1] neg_hi:[0,0,1]
	v_pk_fma_f32 v[168:169], v[46:47], v[168:169], v[176:177]
	v_pk_fma_f32 v[154:155], v[48:49], v[154:155], v[170:171] neg_lo:[0,0,1] neg_hi:[0,0,1]
	v_pk_fma_f32 v[166:167], v[48:49], v[166:167], v[174:175]
	v_cvt_pk_bf16_f32 v164, v164, v165
	v_cvt_pk_bf16_f32 v165, v154, v155
	v_cvt_pk_bf16_f32 v168, v168, v169
	s_nop 0
	v_cvt_pk_bf16_f32 v169, v166, v167
	v_pk_mul_f32 v[154:155], v[138:139], v[210:211] op_sel_hi:[0,1]
	v_pk_mul_f32 v[166:167], v[138:139], v[208:209] op_sel_hi:[0,1]
	v_pk_mul_f32 v[170:171], v[138:139], v[214:215] op_sel_hi:[0,1]
	v_pk_mul_f32 v[172:173], v[138:139], v[212:213] op_sel_hi:[0,1]
	v_pk_mul_f32 v[174:175], v[36:37], v[170:171]
	v_pk_mul_f32 v[176:177], v[34:35], v[172:173]
	v_pk_mul_f32 v[170:171], v[44:45], v[170:171]
	v_pk_mul_f32 v[172:173], v[42:43], v[172:173]
	v_pk_fma_f32 v[174:175], v[44:45], v[154:155], v[174:175] neg_lo:[0,0,1] neg_hi:[0,0,1]
	v_pk_fma_f32 v[176:177], v[42:43], v[166:167], v[176:177] neg_lo:[0,0,1] neg_hi:[0,0,1]
	v_pk_fma_f32 v[154:155], v[36:37], v[154:155], v[170:171]
	v_pk_fma_f32 v[170:171], v[34:35], v[166:167], v[172:173]
	v_cvt_pk_bf16_f32 v166, v176, v177
	v_cvt_pk_bf16_f32 v167, v174, v175
	s_nop 0
	v_cvt_pk_bf16_f32 v170, v170, v171
	v_cvt_pk_bf16_f32 v171, v154, v155
	global_store_dwordx4 v[182:183], v[164:167], off offset:2048
	global_store_dwordx4 v[182:183], v[168:171], off offset:2112
	s_nop 0
	s_waitcnt vmcnt(10)
	v_pk_mul_f32 v[164:165], v[138:139], v[216:217] op_sel_hi:[0,1]
	v_pk_mul_f32 v[168:169], v[138:139], v[220:221] op_sel_hi:[0,1]
	v_pk_mul_f32 v[154:155], v[138:139], v[218:219] op_sel_hi:[0,1]
	v_pk_mul_f32 v[166:167], v[138:139], v[222:223] op_sel_hi:[0,1]
	v_pk_mul_f32 v[172:173], v[22:23], v[168:169]
	v_pk_mul_f32 v[176:177], v[22:23], v[164:165]
	v_pk_mul_f32 v[170:171], v[24:25], v[166:167]
	v_pk_mul_f32 v[174:175], v[24:25], v[154:155]
	v_pk_fma_f32 v[164:165], v[30:31], v[164:165], v[172:173] neg_lo:[0,0,1] neg_hi:[0,0,1]
	v_pk_fma_f32 v[168:169], v[30:31], v[168:169], v[176:177]
	v_pk_fma_f32 v[154:155], v[32:33], v[154:155], v[170:171] neg_lo:[0,0,1] neg_hi:[0,0,1]
	v_pk_fma_f32 v[166:167], v[32:33], v[166:167], v[174:175]
	v_cvt_pk_bf16_f32 v164, v164, v165
	v_cvt_pk_bf16_f32 v165, v154, v155
	v_cvt_pk_bf16_f32 v168, v168, v169
	s_nop 0
	v_cvt_pk_bf16_f32 v169, v166, v167
	v_pk_mul_f32 v[154:155], v[138:139], v[226:227] op_sel_hi:[0,1]
	v_pk_mul_f32 v[166:167], v[138:139], v[224:225] op_sel_hi:[0,1]
	v_pk_mul_f32 v[170:171], v[138:139], v[230:231] op_sel_hi:[0,1]
	v_pk_mul_f32 v[172:173], v[138:139], v[228:229] op_sel_hi:[0,1]
	v_pk_mul_f32 v[174:175], v[20:21], v[170:171]
	v_pk_mul_f32 v[176:177], v[18:19], v[172:173]
	v_pk_mul_f32 v[170:171], v[28:29], v[170:171]
	v_pk_mul_f32 v[172:173], v[26:27], v[172:173]
	v_pk_fma_f32 v[174:175], v[28:29], v[154:155], v[174:175] neg_lo:[0,0,1] neg_hi:[0,0,1]
	v_pk_fma_f32 v[176:177], v[26:27], v[166:167], v[176:177] neg_lo:[0,0,1] neg_hi:[0,0,1]
	v_pk_fma_f32 v[154:155], v[20:21], v[154:155], v[170:171]
	v_pk_fma_f32 v[170:171], v[18:19], v[166:167], v[172:173]
	v_cvt_pk_bf16_f32 v166, v176, v177
	v_cvt_pk_bf16_f32 v167, v174, v175
	s_nop 0
	v_cvt_pk_bf16_f32 v170, v170, v171
	v_cvt_pk_bf16_f32 v171, v154, v155
	global_store_dwordx4 v[148:149], v[164:167], off
	global_store_dwordx4 v[148:149], v[168:171], off offset:64
	s_nop 0
	s_waitcnt vmcnt(6)
	v_pk_mul_f32 v[164:165], v[138:139], v[232:233] op_sel_hi:[0,1]
	v_pk_mul_f32 v[168:169], v[138:139], v[236:237] op_sel_hi:[0,1]
	v_pk_mul_f32 v[154:155], v[138:139], v[234:235] op_sel_hi:[0,1]
	v_pk_mul_f32 v[166:167], v[138:139], v[238:239] op_sel_hi:[0,1]
	v_pk_mul_f32 v[172:173], v[6:7], v[168:169]
	v_pk_mul_f32 v[176:177], v[6:7], v[164:165]
	v_pk_mul_f32 v[170:171], v[8:9], v[166:167]
	v_pk_mul_f32 v[174:175], v[8:9], v[154:155]
	v_pk_fma_f32 v[164:165], v[14:15], v[164:165], v[172:173] neg_lo:[0,0,1] neg_hi:[0,0,1]
	v_pk_fma_f32 v[168:169], v[14:15], v[168:169], v[176:177]
	v_pk_fma_f32 v[154:155], v[16:17], v[154:155], v[170:171] neg_lo:[0,0,1] neg_hi:[0,0,1]
	v_pk_fma_f32 v[166:167], v[16:17], v[166:167], v[174:175]
	v_cvt_pk_bf16_f32 v164, v164, v165
	v_cvt_pk_bf16_f32 v165, v154, v155
	v_cvt_pk_bf16_f32 v168, v168, v169
	s_nop 0
	v_cvt_pk_bf16_f32 v169, v166, v167
	s_nop 0
	v_pk_mul_f32 v[154:155], v[138:139], v[242:243] op_sel_hi:[0,1]
	v_pk_mul_f32 v[152:153], v[138:139], v[246:247] op_sel_hi:[0,1]
	v_pk_mul_f32 v[150:151], v[138:139], v[244:245] op_sel_hi:[0,1]
	v_pk_mul_f32 v[166:167], v[138:139], v[240:241] op_sel_hi:[0,1]
	v_pk_mul_f32 v[170:171], v[4:5], v[152:153]
	v_pk_mul_f32 v[172:173], v[2:3], v[150:151]
	v_pk_mul_f32 v[150:151], v[10:11], v[150:151]
	v_pk_mul_f32 v[152:153], v[12:13], v[152:153]
	v_pk_fma_f32 v[170:171], v[12:13], v[154:155], v[170:171] neg_lo:[0,0,1] neg_hi:[0,0,1]
	v_pk_fma_f32 v[172:173], v[10:11], v[166:167], v[172:173] neg_lo:[0,0,1] neg_hi:[0,0,1]
	v_pk_fma_f32 v[150:151], v[2:3], v[166:167], v[150:151]
	v_cvt_pk_bf16_f32 v166, v172, v173
	v_cvt_pk_bf16_f32 v167, v170, v171
	v_pk_fma_f32 v[152:153], v[4:5], v[154:155], v[152:153]
	v_cvt_pk_bf16_f32 v170, v150, v151
	s_nop 0
	v_cvt_pk_bf16_f32 v171, v152, v153
	global_store_dwordx4 v[148:149], v[164:167], off offset:2048
	global_store_dwordx4 v[148:149], v[168:171], off offset:2112

	.amdhsa_kernel _Z6mk_fwd4Args
		.amdhsa_group_segment_fixed_size 0
		.amdhsa_private_segment_fixed_size 0
		.amdhsa_kernarg_size 384
		.amdhsa_user_sgpr_count 2
		.amdhsa_user_sgpr_dispatch_ptr 0
		.amdhsa_user_sgpr_queue_ptr 0
		.amdhsa_user_sgpr_kernarg_segment_ptr 1
		.amdhsa_user_sgpr_dispatch_id 0
		.amdhsa_user_sgpr_kernarg_preload_length 0
		.amdhsa_user_sgpr_kernarg_preload_offset 0
		.amdhsa_user_sgpr_private_segment_size 0
		.amdhsa_uses_dynamic_stack 0
		.amdhsa_enable_private_segment 0
		.amdhsa_system_sgpr_workgroup_id_x 1
		.amdhsa_system_sgpr_workgroup_id_y 0
		.amdhsa_system_sgpr_workgroup_id_z 0
		.amdhsa_system_sgpr_workgroup_info 0
		.amdhsa_system_vgpr_workitem_id 0
		.amdhsa_next_free_vgpr 256
		.amdhsa_next_free_sgpr 102
		.amdhsa_accum_offset 256
		.amdhsa_reserve_vcc 1
		.amdhsa_float_round_mode_32 0
		.amdhsa_float_round_mode_16_64 0
		.amdhsa_float_denorm_mode_32 3
		.amdhsa_float_denorm_mode_16_64 3
		.amdhsa_dx10_clamp 1
		.amdhsa_ieee_mode 1
		.amdhsa_fp16_overflow 0
		.amdhsa_tg_split 0
		.amdhsa_exception_fp_ieee_invalid_op 0
		.amdhsa_exception_fp_denorm_src 0
		.amdhsa_exception_fp_ieee_div_zero 0
		.amdhsa_exception_fp_ieee_overflow 0
		.amdhsa_exception_fp_ieee_underflow 0
		.amdhsa_exception_fp_ieee_inexact 0
		.amdhsa_exception_int_div_zero 0
	.end_amdhsa_kernel
